# attention unrolled context-tile copies: the 8 K-fragment ds_read_b128 of a tile issued up front with counted lgkmcnt (6 sites)
# speedup vs baseline: 1.0087x; 1.0087x over previous
; #define LAS __attribute__((address_space(3)))
; template <bool SWA>
; DI void attn_phase(const Ctx& a, LAS unsigned char* lds) {
;     ...
;                 f32x4 sc[4];
; #pragma unroll
;                 for (int jt = 0; jt < 4; ++jt) {
;                     const int row = 16 * jt + fr; const int sw = (row >> 1) & 7;
;                     const bf16x8 k0 = *(const LAS bf16x8*)(lds + AT_K + buf * 8192 + row * 128 + ((fq ^ sw) << 4));
;                     const bf16x8 k1 = *(const LAS bf16x8*)(lds + AT_K + buf * 8192 + row * 128 + (((4 + fq) ^ sw) << 4));
;                     f32x4 acc = (f32x4){0.f, 0.f, 0.f, 0.f}; acc = MFMA16(k0, qf[0], acc); acc = MFMA16(k1, qf[1], acc); sc[jt] = acc;
;                 }
;                 float sv[16]; bool ok[16];
; #pragma unroll
;                 for (int jt = 0; jt < 4; ++jt)
; #pragma unroll
;                     for (int rr = 0; rr < 4; ++rr) {
;                         bool valid = true;
;                         if (SWA && local) { const int dd = tkey0 + 16 * jt + 4 * fq + rr - (tq0 + fr); valid = (dd <= 128) && (dd >= -128); }
;                         sv[jt * 4 + rr] = valid ? sc[jt][rr] : -1e30f; ok[jt * 4 + rr] = valid;
;                     }
;                 float cmax = sv[0];
; #pragma unroll
;                 for (int e = 1; e < 16; ++e) cmax = fmaxf(cmax, sv[e]);
;                 cmax = fmaxf(cmax, shx(cmax, 16, lane)); cmax = fmaxf(cmax, shx(cmax, 32, lane));
;                 const float m_new = fmaxf(m_run, cmax);
;                 const float alpha = __builtin_amdgcn_exp2f((m_run - m_new) * LOG2E);
;                 float p[16], psum = 0.f;
; #pragma unroll
;                 for (int e = 0; e < 16; ++e) { p[e] = ok[e] ? __builtin_amdgcn_exp2f((sv[e] - m_new) * LOG2E) : 0.f; psum += p[e]; }
;                 l_run = l_run * alpha + psum; m_run = m_new;
;                 u32x4 pw0, pw1; pw0.x = pk2(p[0], p[1]); pw0.y = pk2(p[2], p[3]); pw0.z = pk2(p[4], p[5]); pw0.w = pk2(p[6], p[7]);
;                 pw1.x = pk2(p[8], p[9]); pw1.y = pk2(p[10], p[11]); pw1.z = pk2(p[12], p[13]); pw1.w = pk2(p[14], p[15]);
;                 const bf16x8 pf0 = __builtin_bit_cast(bf16x8, pw0), pf1 = __builtin_bit_cast(bf16x8, pw1);
;                 if (__builtin_amdgcn_ballot_w64(alpha != 1.f) != 0ull) {
; #pragma unroll
;                     for (int dt = 0; dt < 4; ++dt) o[dt] = o[dt] * alpha;
;                 }
.LBB0_85:
	ds_read_b128 v[164:167], v79 offset:8192
	ds_read_b128 v[168:171], v80 offset:8192
	ds_read_b128 v[172:175], v79 offset:10240
	ds_read_b128 v[176:179], v80 offset:10240
	ds_read_b128 v[180:183], v79 offset:12288
	ds_read_b128 v[184:187], v80 offset:12288
	ds_read_b128 v[192:195], v79 offset:14336
	ds_read_b128 v[196:199], v80 offset:14336
	s_waitcnt lgkmcnt(6)
	v_mfma_f32_16x16x32_bf16 v[24:27], v[164:167], v[12:15], 0
	v_mfma_f32_16x16x32_bf16 v[24:27], v[168:171], v[16:19], v[24:27]
	s_waitcnt lgkmcnt(4)
	v_mfma_f32_16x16x32_bf16 v[28:31], v[172:175], v[12:15], 0
	v_mfma_f32_16x16x32_bf16 v[28:31], v[176:179], v[16:19], v[28:31]
	s_waitcnt lgkmcnt(2)
	v_mfma_f32_16x16x32_bf16 v[32:35], v[180:183], v[12:15], 0
	v_mfma_f32_16x16x32_bf16 v[32:35], v[184:187], v[16:19], v[32:35]
	s_waitcnt lgkmcnt(0)
	v_mfma_f32_16x16x32_bf16 v[36:39], v[192:195], v[12:15], 0
	v_mfma_f32_16x16x32_bf16 v[36:39], v[196:199], v[16:19], v[36:39]
	v_max_f32_e32 v84, v25, v25
	v_max_f32_e32 v85, v24, v24
	v_max_f32_e32 v84, v85, v84
	v_max3_f32 v84, v84, v26, v27
	v_max3_f32 v84, v84, v28, v29
	v_max3_f32 v84, v84, v30, v31
	v_max3_f32 v84, v84, v32, v33
	v_max3_f32 v84, v84, v34, v35
	v_max3_f32 v84, v84, v36, v37
	v_max3_f32 v84, v84, v38, v39
	ds_bpermute_b32 v85, v68, v84
	s_waitcnt lgkmcnt(0)
	v_max_f32_e32 v85, v85, v85
	v_max_f32_e32 v84, v84, v85
	ds_bpermute_b32 v85, v69, v84
	s_waitcnt lgkmcnt(0)
	v_max3_f32 v85, v60, v84, v85
	v_sub_f32_e32 v60, v60, v85
	v_mul_f32_e32 v60, 0x3fb8aa3b, v60
	v_exp_f32_e32 v60, v60
	s_nop 0
	v_cmp_neq_f32_e32 vcc, 1.0, v60
	s_cbranch_vccz .LBB0_87
	v_pk_mul_f32 v[22:23], v[22:23], v[60:61] op_sel_hi:[1,0]
	v_pk_mul_f32 v[20:21], v[20:21], v[60:61] op_sel_hi:[1,0]
	v_pk_mul_f32 v[10:11], v[10:11], v[60:61] op_sel_hi:[1,0]
	v_pk_mul_f32 v[8:9], v[8:9], v[60:61] op_sel_hi:[1,0]
	v_pk_mul_f32 v[6:7], v[6:7], v[60:61] op_sel_hi:[1,0]
	v_pk_mul_f32 v[4:5], v[4:5], v[60:61] op_sel_hi:[1,0]
	v_pk_mul_f32 v[2:3], v[2:3], v[60:61] op_sel_hi:[1,0]
	v_pk_mul_f32 v[0:1], v[0:1], v[60:61] op_sel_hi:[1,0]

; #define LAS __attribute__((address_space(3)))
; template <bool SWA>
; DI void attn_phase(const Ctx& a, LAS unsigned char* lds) {
;     ...
;                 f32x4 sc[4];
; #pragma unroll
;                 for (int jt = 0; jt < 4; ++jt) {
;                     const int row = 16 * jt + fr; const int sw = (row >> 1) & 7;
;                     const bf16x8 k0 = *(const LAS bf16x8*)(lds + AT_K + buf * 8192 + row * 128 + ((fq ^ sw) << 4));
;                     const bf16x8 k1 = *(const LAS bf16x8*)(lds + AT_K + buf * 8192 + row * 128 + (((4 + fq) ^ sw) << 4));
;                     f32x4 acc = (f32x4){0.f, 0.f, 0.f, 0.f}; acc = MFMA16(k0, qf[0], acc); acc = MFMA16(k1, qf[1], acc); sc[jt] = acc;
;                 }
;                 float sv[16]; bool ok[16];
; #pragma unroll
;                 for (int jt = 0; jt < 4; ++jt)
; #pragma unroll
;                     for (int rr = 0; rr < 4; ++rr) {
;                         bool valid = true;
;                         if (SWA && local) { const int dd = tkey0 + 16 * jt + 4 * fq + rr - (tq0 + fr); valid = (dd <= 128) && (dd >= -128); }
;                         sv[jt * 4 + rr] = valid ? sc[jt][rr] : -1e30f; ok[jt * 4 + rr] = valid;
;                     }
;                 float cmax = sv[0];
; #pragma unroll
;                 for (int e = 1; e < 16; ++e) cmax = fmaxf(cmax, sv[e]);
;                 cmax = fmaxf(cmax, shx(cmax, 16, lane)); cmax = fmaxf(cmax, shx(cmax, 32, lane));
;                 const float m_new = fmaxf(m_run, cmax);
;                 const float alpha = __builtin_amdgcn_exp2f((m_run - m_new) * LOG2E);
;                 float p[16], psum = 0.f;
; #pragma unroll
;                 for (int e = 0; e < 16; ++e) { p[e] = ok[e] ? __builtin_amdgcn_exp2f((sv[e] - m_new) * LOG2E) : 0.f; psum += p[e]; }
;                 l_run = l_run * alpha + psum; m_run = m_new;
;                 u32x4 pw0, pw1; pw0.x = pk2(p[0], p[1]); pw0.y = pk2(p[2], p[3]); pw0.z = pk2(p[4], p[5]); pw0.w = pk2(p[6], p[7]);
;                 pw1.x = pk2(p[8], p[9]); pw1.y = pk2(p[10], p[11]); pw1.z = pk2(p[12], p[13]); pw1.w = pk2(p[14], p[15]);
;                 const bf16x8 pf0 = __builtin_bit_cast(bf16x8, pw0), pf1 = __builtin_bit_cast(bf16x8, pw1);
;                 if (__builtin_amdgcn_ballot_w64(alpha != 1.f) != 0ull) {
; #pragma unroll
;                     for (int dt = 0; dt < 4; ++dt) o[dt] = o[dt] * alpha;
;                 }
.LBB0_94:
	ds_read_b128 v[164:167], v79 offset:16384
	ds_read_b128 v[168:171], v80 offset:16384
	ds_read_b128 v[172:175], v79 offset:18432
	ds_read_b128 v[176:179], v80 offset:18432
	ds_read_b128 v[180:183], v79 offset:20480
	ds_read_b128 v[184:187], v80 offset:20480
	ds_read_b128 v[192:195], v79 offset:22528
	ds_read_b128 v[196:199], v80 offset:22528
	s_waitcnt lgkmcnt(6)
	v_mfma_f32_16x16x32_bf16 v[24:27], v[164:167], v[12:15], 0
	v_mfma_f32_16x16x32_bf16 v[24:27], v[168:171], v[16:19], v[24:27]
	s_waitcnt lgkmcnt(4)
	v_mfma_f32_16x16x32_bf16 v[28:31], v[172:175], v[12:15], 0
	s_nop 3
	v_max_f32_e32 v60, v25, v25
	v_max_f32_e32 v81, v24, v24
	v_max_f32_e32 v60, v81, v60
	v_mfma_f32_16x16x32_bf16 v[28:31], v[176:179], v[16:19], v[28:31]
	v_max3_f32 v60, v60, v26, v27
	s_waitcnt lgkmcnt(2)
	v_mfma_f32_16x16x32_bf16 v[32:35], v[180:183], v[12:15], 0
	s_nop 2
	v_max3_f32 v60, v60, v28, v29
	v_max3_f32 v60, v60, v30, v31
	v_mfma_f32_16x16x32_bf16 v[32:35], v[184:187], v[16:19], v[32:35]
	s_waitcnt lgkmcnt(0)
	v_mfma_f32_16x16x32_bf16 v[36:39], v[192:195], v[12:15], 0
	s_nop 3
	v_max3_f32 v60, v60, v32, v33
	v_max3_f32 v60, v60, v34, v35
	v_mfma_f32_16x16x32_bf16 v[36:39], v[196:199], v[16:19], v[36:39]
	s_nop 7
	v_max3_f32 v60, v60, v36, v37
	v_max3_f32 v60, v60, v38, v39
	ds_bpermute_b32 v81, v68, v60
	s_waitcnt lgkmcnt(0)
	v_max_f32_e32 v81, v81, v81
	v_max_f32_e32 v60, v60, v81
	ds_bpermute_b32 v81, v69, v60
	s_waitcnt lgkmcnt(0)
	v_max3_f32 v82, v85, v60, v81
	v_sub_f32_e32 v60, v85, v82
	v_mul_f32_e32 v60, 0x3fb8aa3b, v60
	v_exp_f32_e32 v60, v60
	s_nop 0
	v_cmp_neq_f32_e32 vcc, 1.0, v60
	s_cbranch_vccz .LBB0_96
	v_pk_mul_f32 v[22:23], v[22:23], v[60:61] op_sel_hi:[1,0]
	v_pk_mul_f32 v[20:21], v[20:21], v[60:61] op_sel_hi:[1,0]
	v_pk_mul_f32 v[10:11], v[10:11], v[60:61] op_sel_hi:[1,0]
	v_pk_mul_f32 v[8:9], v[8:9], v[60:61] op_sel_hi:[1,0]
	v_pk_mul_f32 v[6:7], v[6:7], v[60:61] op_sel_hi:[1,0]
	v_pk_mul_f32 v[4:5], v[4:5], v[60:61] op_sel_hi:[1,0]
	v_pk_mul_f32 v[2:3], v[2:3], v[60:61] op_sel_hi:[1,0]
	v_pk_mul_f32 v[0:1], v[0:1], v[60:61] op_sel_hi:[1,0]

; #define LAS __attribute__((address_space(3)))
; template <bool SWA>
; DI void attn_phase(const Ctx& a, LAS unsigned char* lds) {
;     ...
;                 f32x4 sc[4];
; #pragma unroll
;                 for (int jt = 0; jt < 4; ++jt) {
;                     const int row = 16 * jt + fr; const int sw = (row >> 1) & 7;
;                     const bf16x8 k0 = *(const LAS bf16x8*)(lds + AT_K + buf * 8192 + row * 128 + ((fq ^ sw) << 4));
;                     const bf16x8 k1 = *(const LAS bf16x8*)(lds + AT_K + buf * 8192 + row * 128 + (((4 + fq) ^ sw) << 4));
;                     f32x4 acc = (f32x4){0.f, 0.f, 0.f, 0.f}; acc = MFMA16(k0, qf[0], acc); acc = MFMA16(k1, qf[1], acc); sc[jt] = acc;
;                 }
;                 float sv[16]; bool ok[16];
; #pragma unroll
;                 for (int jt = 0; jt < 4; ++jt)
; #pragma unroll
;                     for (int rr = 0; rr < 4; ++rr) {
;                         bool valid = true;
;                         if (SWA && local) { const int dd = tkey0 + 16 * jt + 4 * fq + rr - (tq0 + fr); valid = (dd <= 128) && (dd >= -128); }
;                         sv[jt * 4 + rr] = valid ? sc[jt][rr] : -1e30f; ok[jt * 4 + rr] = valid;
;                     }
;                 float cmax = sv[0];
; #pragma unroll
;                 for (int e = 1; e < 16; ++e) cmax = fmaxf(cmax, sv[e]);
;                 cmax = fmaxf(cmax, shx(cmax, 16, lane)); cmax = fmaxf(cmax, shx(cmax, 32, lane));
;                 const float m_new = fmaxf(m_run, cmax);
;                 const float alpha = __builtin_amdgcn_exp2f((m_run - m_new) * LOG2E);
;                 float p[16], psum = 0.f;
; #pragma unroll
;                 for (int e = 0; e < 16; ++e) { p[e] = ok[e] ? __builtin_amdgcn_exp2f((sv[e] - m_new) * LOG2E) : 0.f; psum += p[e]; }
;                 l_run = l_run * alpha + psum; m_run = m_new;
;                 u32x4 pw0, pw1; pw0.x = pk2(p[0], p[1]); pw0.y = pk2(p[2], p[3]); pw0.z = pk2(p[4], p[5]); pw0.w = pk2(p[6], p[7]);
;                 pw1.x = pk2(p[8], p[9]); pw1.y = pk2(p[10], p[11]); pw1.z = pk2(p[12], p[13]); pw1.w = pk2(p[14], p[15]);
;                 const bf16x8 pf0 = __builtin_bit_cast(bf16x8, pw0), pf1 = __builtin_bit_cast(bf16x8, pw1);
;                 if (__builtin_amdgcn_ballot_w64(alpha != 1.f) != 0ull) {
; #pragma unroll
;                     for (int dt = 0; dt < 4; ++dt) o[dt] = o[dt] * alpha;
;                 }
.LBB0_103:
	ds_read_b128 v[164:167], v79
	ds_read_b128 v[168:171], v80
	ds_read_b128 v[172:175], v79 offset:2048
	ds_read_b128 v[176:179], v80 offset:2048
	ds_read_b128 v[180:183], v79 offset:4096
	ds_read_b128 v[184:187], v80 offset:4096
	ds_read_b128 v[192:195], v79 offset:6144
	ds_read_b128 v[196:199], v80 offset:6144
	s_waitcnt lgkmcnt(6)
	v_mfma_f32_16x16x32_bf16 v[24:27], v[164:167], v[12:15], 0
	v_mfma_f32_16x16x32_bf16 v[24:27], v[168:171], v[16:19], v[24:27]
	s_waitcnt lgkmcnt(4)
	v_mfma_f32_16x16x32_bf16 v[28:31], v[172:175], v[12:15], 0
	s_nop 3
	v_max_f32_e32 v60, v25, v25
	v_mfma_f32_16x16x32_bf16 v[28:31], v[176:179], v[16:19], v[28:31]
	s_waitcnt lgkmcnt(2)
	v_mfma_f32_16x16x32_bf16 v[32:35], v[180:183], v[12:15], 0
	v_mfma_f32_16x16x32_bf16 v[32:35], v[184:187], v[16:19], v[32:35]
	v_max_f32_e32 v79, v24, v24
	v_max_f32_e32 v60, v79, v60
	s_waitcnt lgkmcnt(0)
	v_mfma_f32_16x16x32_bf16 v[36:39], v[192:195], v[12:15], 0
	v_max3_f32 v60, v60, v26, v27
	v_max3_f32 v60, v60, v28, v29
	v_max3_f32 v60, v60, v30, v31
	v_mfma_f32_16x16x32_bf16 v[36:39], v[196:199], v[16:19], v[36:39]
	v_max3_f32 v60, v60, v32, v33
	v_max3_f32 v60, v60, v34, v35
	s_nop 5
	v_max3_f32 v60, v60, v36, v37
	v_max3_f32 v60, v60, v38, v39
	ds_bpermute_b32 v79, v68, v60
	s_waitcnt lgkmcnt(0)
	v_max_f32_e32 v79, v79, v79
	v_max_f32_e32 v60, v60, v79
	ds_bpermute_b32 v79, v69, v60
	s_waitcnt lgkmcnt(0)
	v_max3_f32 v79, v82, v60, v79
	v_sub_f32_e32 v60, v82, v79
	v_mul_f32_e32 v60, 0x3fb8aa3b, v60
	v_exp_f32_e32 v60, v60
	s_nop 0
	v_cmp_neq_f32_e32 vcc, 1.0, v60
	s_cbranch_vccz .LBB0_105
	v_pk_mul_f32 v[22:23], v[22:23], v[60:61] op_sel_hi:[1,0]
	v_pk_mul_f32 v[20:21], v[20:21], v[60:61] op_sel_hi:[1,0]
	v_pk_mul_f32 v[10:11], v[10:11], v[60:61] op_sel_hi:[1,0]
	v_pk_mul_f32 v[8:9], v[8:9], v[60:61] op_sel_hi:[1,0]
	v_pk_mul_f32 v[6:7], v[6:7], v[60:61] op_sel_hi:[1,0]
	v_pk_mul_f32 v[4:5], v[4:5], v[60:61] op_sel_hi:[1,0]
	v_pk_mul_f32 v[2:3], v[2:3], v[60:61] op_sel_hi:[1,0]
	v_pk_mul_f32 v[0:1], v[0:1], v[60:61] op_sel_hi:[1,0]

; #define LAS __attribute__((address_space(3)))
; template <bool SWA>
; DI void attn_phase(const Ctx& a, LAS unsigned char* lds) {
;     ...
;                 f32x4 sc[4];
; #pragma unroll
;                 for (int jt = 0; jt < 4; ++jt) {
;                     const int row = 16 * jt + fr; const int sw = (row >> 1) & 7;
;                     const bf16x8 k0 = *(const LAS bf16x8*)(lds + AT_K + buf * 8192 + row * 128 + ((fq ^ sw) << 4));
;                     const bf16x8 k1 = *(const LAS bf16x8*)(lds + AT_K + buf * 8192 + row * 128 + (((4 + fq) ^ sw) << 4));
;                     f32x4 acc = (f32x4){0.f, 0.f, 0.f, 0.f}; acc = MFMA16(k0, qf[0], acc); acc = MFMA16(k1, qf[1], acc); sc[jt] = acc;
;                 }
;                 float sv[16]; bool ok[16];
; #pragma unroll
;                 for (int jt = 0; jt < 4; ++jt)
; #pragma unroll
;                     for (int rr = 0; rr < 4; ++rr) {
;                         bool valid = true;
;                         if (SWA && local) { const int dd = tkey0 + 16 * jt + 4 * fq + rr - (tq0 + fr); valid = (dd <= 128) && (dd >= -128); }
;                         sv[jt * 4 + rr] = valid ? sc[jt][rr] : -1e30f; ok[jt * 4 + rr] = valid;
;                     }
;                 float cmax = sv[0];
; #pragma unroll
;                 for (int e = 1; e < 16; ++e) cmax = fmaxf(cmax, sv[e]);
;                 cmax = fmaxf(cmax, shx(cmax, 16, lane)); cmax = fmaxf(cmax, shx(cmax, 32, lane));
;                 const float m_new = fmaxf(m_run, cmax);
;                 const float alpha = __builtin_amdgcn_exp2f((m_run - m_new) * LOG2E);
;                 float p[16], psum = 0.f;
; #pragma unroll
;                 for (int e = 0; e < 16; ++e) { p[e] = ok[e] ? __builtin_amdgcn_exp2f((sv[e] - m_new) * LOG2E) : 0.f; psum += p[e]; }
;                 l_run = l_run * alpha + psum; m_run = m_new;
;                 u32x4 pw0, pw1; pw0.x = pk2(p[0], p[1]); pw0.y = pk2(p[2], p[3]); pw0.z = pk2(p[4], p[5]); pw0.w = pk2(p[6], p[7]);
;                 pw1.x = pk2(p[8], p[9]); pw1.y = pk2(p[10], p[11]); pw1.z = pk2(p[12], p[13]); pw1.w = pk2(p[14], p[15]);
;                 const bf16x8 pf0 = __builtin_bit_cast(bf16x8, pw0), pf1 = __builtin_bit_cast(bf16x8, pw1);
;                 if (__builtin_amdgcn_ballot_w64(alpha != 1.f) != 0ull) {
; #pragma unroll
;                     for (int dt = 0; dt < 4; ++dt) o[dt] = o[dt] * alpha;
;                 }
.LBB0_151:
	ds_read_b128 v[164:167], v75 offset:8192
	ds_read_b128 v[168:171], v76 offset:8192
	ds_read_b128 v[172:175], v75 offset:10240
	ds_read_b128 v[176:179], v76 offset:10240
	ds_read_b128 v[180:183], v75 offset:12288
	ds_read_b128 v[184:187], v76 offset:12288
	ds_read_b128 v[192:195], v75 offset:14336
	ds_read_b128 v[196:199], v76 offset:14336
	s_waitcnt lgkmcnt(6)
	v_mfma_f32_16x16x32_bf16 v[24:27], v[164:167], v[0:3], 0
	v_mfma_f32_16x16x32_bf16 v[24:27], v[168:171], v[4:7], v[24:27]
	s_waitcnt lgkmcnt(4)
	v_mfma_f32_16x16x32_bf16 v[28:31], v[172:175], v[0:3], 0
	v_mfma_f32_16x16x32_bf16 v[28:31], v[176:179], v[4:7], v[28:31]
	s_waitcnt lgkmcnt(2)
	v_mfma_f32_16x16x32_bf16 v[32:35], v[180:183], v[0:3], 0
	v_mfma_f32_16x16x32_bf16 v[32:35], v[184:187], v[4:7], v[32:35]
	s_waitcnt lgkmcnt(0)
	v_mfma_f32_16x16x32_bf16 v[36:39], v[192:195], v[0:3], 0
	v_mfma_f32_16x16x32_bf16 v[36:39], v[196:199], v[4:7], v[36:39]
	v_max_f32_e32 v86, v25, v25
	v_max_f32_e32 v87, v24, v24
	v_max_f32_e32 v86, v87, v86
	v_max3_f32 v86, v86, v26, v27
	v_max3_f32 v86, v86, v28, v29
	v_max3_f32 v86, v86, v30, v31
	v_max3_f32 v86, v86, v32, v33
	v_max3_f32 v86, v86, v34, v35
	v_max3_f32 v86, v86, v36, v37
	v_max3_f32 v86, v86, v38, v39
	ds_bpermute_b32 v87, v69, v86
	s_waitcnt lgkmcnt(0)
	v_max_f32_e32 v87, v87, v87
	v_max_f32_e32 v86, v86, v87
	ds_bpermute_b32 v87, v70, v86
	s_waitcnt lgkmcnt(0)
	v_max3_f32 v87, v58, v86, v87
	v_sub_f32_e32 v58, v58, v87
	v_mul_f32_e32 v58, 0x3fb8aa3b, v58
	v_exp_f32_e32 v58, v58
	s_nop 0
	v_cmp_neq_f32_e32 vcc, 1.0, v58
	s_cbranch_vccz .LBB0_153
	v_pk_mul_f32 v[10:11], v[10:11], v[58:59] op_sel_hi:[1,0]
	v_pk_mul_f32 v[8:9], v[8:9], v[58:59] op_sel_hi:[1,0]
	v_pk_mul_f32 v[22:23], v[22:23], v[58:59] op_sel_hi:[1,0]
	v_pk_mul_f32 v[20:21], v[20:21], v[58:59] op_sel_hi:[1,0]
	v_pk_mul_f32 v[18:19], v[18:19], v[58:59] op_sel_hi:[1,0]
	v_pk_mul_f32 v[16:17], v[16:17], v[58:59] op_sel_hi:[1,0]
	v_pk_mul_f32 v[14:15], v[14:15], v[58:59] op_sel_hi:[1,0]
	v_pk_mul_f32 v[12:13], v[12:13], v[58:59] op_sel_hi:[1,0]

; #define LAS __attribute__((address_space(3)))
; template <bool SWA>
; DI void attn_phase(const Ctx& a, LAS unsigned char* lds) {
;     ...
;                 f32x4 sc[4];
; #pragma unroll
;                 for (int jt = 0; jt < 4; ++jt) {
;                     const int row = 16 * jt + fr; const int sw = (row >> 1) & 7;
;                     const bf16x8 k0 = *(const LAS bf16x8*)(lds + AT_K + buf * 8192 + row * 128 + ((fq ^ sw) << 4));
;                     const bf16x8 k1 = *(const LAS bf16x8*)(lds + AT_K + buf * 8192 + row * 128 + (((4 + fq) ^ sw) << 4));
;                     f32x4 acc = (f32x4){0.f, 0.f, 0.f, 0.f}; acc = MFMA16(k0, qf[0], acc); acc = MFMA16(k1, qf[1], acc); sc[jt] = acc;
;                 }
;                 float sv[16]; bool ok[16];
; #pragma unroll
;                 for (int jt = 0; jt < 4; ++jt)
; #pragma unroll
;                     for (int rr = 0; rr < 4; ++rr) {
;                         bool valid = true;
;                         if (SWA && local) { const int dd = tkey0 + 16 * jt + 4 * fq + rr - (tq0 + fr); valid = (dd <= 128) && (dd >= -128); }
;                         sv[jt * 4 + rr] = valid ? sc[jt][rr] : -1e30f; ok[jt * 4 + rr] = valid;
;                     }
;                 float cmax = sv[0];
; #pragma unroll
;                 for (int e = 1; e < 16; ++e) cmax = fmaxf(cmax, sv[e]);
;                 cmax = fmaxf(cmax, shx(cmax, 16, lane)); cmax = fmaxf(cmax, shx(cmax, 32, lane));
;                 const float m_new = fmaxf(m_run, cmax);
;                 const float alpha = __builtin_amdgcn_exp2f((m_run - m_new) * LOG2E);
;                 float p[16], psum = 0.f;
; #pragma unroll
;                 for (int e = 0; e < 16; ++e) { p[e] = ok[e] ? __builtin_amdgcn_exp2f((sv[e] - m_new) * LOG2E) : 0.f; psum += p[e]; }
;                 l_run = l_run * alpha + psum; m_run = m_new;
;                 u32x4 pw0, pw1; pw0.x = pk2(p[0], p[1]); pw0.y = pk2(p[2], p[3]); pw0.z = pk2(p[4], p[5]); pw0.w = pk2(p[6], p[7]);
;                 pw1.x = pk2(p[8], p[9]); pw1.y = pk2(p[10], p[11]); pw1.z = pk2(p[12], p[13]); pw1.w = pk2(p[14], p[15]);
;                 const bf16x8 pf0 = __builtin_bit_cast(bf16x8, pw0), pf1 = __builtin_bit_cast(bf16x8, pw1);
;                 if (__builtin_amdgcn_ballot_w64(alpha != 1.f) != 0ull) {
; #pragma unroll
;                     for (int dt = 0; dt < 4; ++dt) o[dt] = o[dt] * alpha;
;                 }
.LBB0_160:
	ds_read_b128 v[164:167], v75 offset:16384
	ds_read_b128 v[168:171], v76 offset:16384
	ds_read_b128 v[172:175], v75 offset:18432
	ds_read_b128 v[176:179], v76 offset:18432
	ds_read_b128 v[180:183], v75 offset:20480
	ds_read_b128 v[184:187], v76 offset:20480
	ds_read_b128 v[192:195], v75 offset:22528
	ds_read_b128 v[196:199], v76 offset:22528
	s_waitcnt lgkmcnt(6)
	v_mfma_f32_16x16x32_bf16 v[24:27], v[164:167], v[0:3], 0
	v_mfma_f32_16x16x32_bf16 v[24:27], v[168:171], v[4:7], v[24:27]
	s_waitcnt lgkmcnt(4)
	v_mfma_f32_16x16x32_bf16 v[28:31], v[172:175], v[0:3], 0
	s_nop 3
	v_max_f32_e32 v49, v25, v25
	v_max_f32_e32 v58, v24, v24
	v_max_f32_e32 v49, v58, v49
	v_mfma_f32_16x16x32_bf16 v[28:31], v[176:179], v[4:7], v[28:31]
	v_max3_f32 v49, v49, v26, v27
	s_waitcnt lgkmcnt(2)
	v_mfma_f32_16x16x32_bf16 v[32:35], v[180:183], v[0:3], 0
	s_nop 2
	v_max3_f32 v49, v49, v28, v29
	v_max3_f32 v49, v49, v30, v31
	v_mfma_f32_16x16x32_bf16 v[32:35], v[184:187], v[4:7], v[32:35]
	s_waitcnt lgkmcnt(0)
	v_mfma_f32_16x16x32_bf16 v[36:39], v[192:195], v[0:3], 0
	s_nop 3
	v_max3_f32 v49, v49, v32, v33
	v_max3_f32 v49, v49, v34, v35
	v_mfma_f32_16x16x32_bf16 v[36:39], v[196:199], v[4:7], v[36:39]
	s_nop 7
	v_max3_f32 v49, v49, v36, v37
	v_max3_f32 v49, v49, v38, v39
	ds_bpermute_b32 v58, v69, v49
	s_waitcnt lgkmcnt(0)
	v_max_f32_e32 v58, v58, v58
	v_max_f32_e32 v49, v49, v58
	ds_bpermute_b32 v58, v70, v49
	s_waitcnt lgkmcnt(0)
	v_max3_f32 v85, v87, v49, v58
	v_sub_f32_e32 v49, v87, v85
	v_mul_f32_e32 v49, 0x3fb8aa3b, v49
	v_exp_f32_e32 v58, v49
	s_nop 0
	v_cmp_neq_f32_e32 vcc, 1.0, v58
	s_cbranch_vccz .LBB0_162
	v_pk_mul_f32 v[14:15], v[14:15], v[58:59] op_sel_hi:[1,0]
	v_pk_mul_f32 v[12:13], v[12:13], v[58:59] op_sel_hi:[1,0]
	v_pk_mul_f32 v[18:19], v[18:19], v[58:59] op_sel_hi:[1,0]
	v_pk_mul_f32 v[16:17], v[16:17], v[58:59] op_sel_hi:[1,0]
	v_pk_mul_f32 v[22:23], v[22:23], v[58:59] op_sel_hi:[1,0]
	v_pk_mul_f32 v[20:21], v[20:21], v[58:59] op_sel_hi:[1,0]
	v_pk_mul_f32 v[10:11], v[10:11], v[58:59] op_sel_hi:[1,0]
	v_pk_mul_f32 v[8:9], v[8:9], v[58:59] op_sel_hi:[1,0]

; #define LAS __attribute__((address_space(3)))
; template <bool SWA>
; DI void attn_phase(const Ctx& a, LAS unsigned char* lds) {
;     ...
;                 f32x4 sc[4];
; #pragma unroll
;                 for (int jt = 0; jt < 4; ++jt) {
;                     const int row = 16 * jt + fr; const int sw = (row >> 1) & 7;
;                     const bf16x8 k0 = *(const LAS bf16x8*)(lds + AT_K + buf * 8192 + row * 128 + ((fq ^ sw) << 4));
;                     const bf16x8 k1 = *(const LAS bf16x8*)(lds + AT_K + buf * 8192 + row * 128 + (((4 + fq) ^ sw) << 4));
;                     f32x4 acc = (f32x4){0.f, 0.f, 0.f, 0.f}; acc = MFMA16(k0, qf[0], acc); acc = MFMA16(k1, qf[1], acc); sc[jt] = acc;
;                 }
;                 float sv[16]; bool ok[16];
; #pragma unroll
;                 for (int jt = 0; jt < 4; ++jt)
; #pragma unroll
;                     for (int rr = 0; rr < 4; ++rr) {
;                         bool valid = true;
;                         if (SWA && local) { const int dd = tkey0 + 16 * jt + 4 * fq + rr - (tq0 + fr); valid = (dd <= 128) && (dd >= -128); }
;                         sv[jt * 4 + rr] = valid ? sc[jt][rr] : -1e30f; ok[jt * 4 + rr] = valid;
;                     }
;                 float cmax = sv[0];
; #pragma unroll
;                 for (int e = 1; e < 16; ++e) cmax = fmaxf(cmax, sv[e]);
;                 cmax = fmaxf(cmax, shx(cmax, 16, lane)); cmax = fmaxf(cmax, shx(cmax, 32, lane));
;                 const float m_new = fmaxf(m_run, cmax);
;                 const float alpha = __builtin_amdgcn_exp2f((m_run - m_new) * LOG2E);
;                 float p[16], psum = 0.f;
; #pragma unroll
;                 for (int e = 0; e < 16; ++e) { p[e] = ok[e] ? __builtin_amdgcn_exp2f((sv[e] - m_new) * LOG2E) : 0.f; psum += p[e]; }
;                 l_run = l_run * alpha + psum; m_run = m_new;
;                 u32x4 pw0, pw1; pw0.x = pk2(p[0], p[1]); pw0.y = pk2(p[2], p[3]); pw0.z = pk2(p[4], p[5]); pw0.w = pk2(p[6], p[7]);
;                 pw1.x = pk2(p[8], p[9]); pw1.y = pk2(p[10], p[11]); pw1.z = pk2(p[12], p[13]); pw1.w = pk2(p[14], p[15]);
;                 const bf16x8 pf0 = __builtin_bit_cast(bf16x8, pw0), pf1 = __builtin_bit_cast(bf16x8, pw1);
;                 if (__builtin_amdgcn_ballot_w64(alpha != 1.f) != 0ull) {
; #pragma unroll
;                     for (int dt = 0; dt < 4; ++dt) o[dt] = o[dt] * alpha;
;                 }
.LBB0_169:
	ds_read_b128 v[164:167], v75
	ds_read_b128 v[168:171], v76
	ds_read_b128 v[172:175], v75 offset:2048
	ds_read_b128 v[176:179], v76 offset:2048
	ds_read_b128 v[180:183], v75 offset:4096
	ds_read_b128 v[184:187], v76 offset:4096
	ds_read_b128 v[192:195], v75 offset:6144
	ds_read_b128 v[196:199], v76 offset:6144
	s_waitcnt lgkmcnt(6)
	v_mfma_f32_16x16x32_bf16 v[24:27], v[164:167], v[0:3], 0
	v_mfma_f32_16x16x32_bf16 v[24:27], v[168:171], v[4:7], v[24:27]
	s_waitcnt lgkmcnt(4)
	v_mfma_f32_16x16x32_bf16 v[28:31], v[172:175], v[0:3], 0
	s_nop 3
	v_max_f32_e32 v49, v25, v25
	v_max_f32_e32 v58, v24, v24
	v_max_f32_e32 v49, v58, v49
	v_mfma_f32_16x16x32_bf16 v[28:31], v[176:179], v[4:7], v[28:31]
	v_max3_f32 v49, v49, v26, v27
	s_waitcnt lgkmcnt(2)
	v_mfma_f32_16x16x32_bf16 v[32:35], v[180:183], v[0:3], 0
	s_nop 2
	v_max3_f32 v49, v49, v28, v29
	v_max3_f32 v49, v49, v30, v31
	v_mfma_f32_16x16x32_bf16 v[32:35], v[184:187], v[4:7], v[32:35]
	s_waitcnt lgkmcnt(0)
	v_mfma_f32_16x16x32_bf16 v[36:39], v[192:195], v[0:3], 0
	s_nop 3
	v_max3_f32 v49, v49, v32, v33
	v_max3_f32 v49, v49, v34, v35
	v_mfma_f32_16x16x32_bf16 v[36:39], v[196:199], v[4:7], v[36:39]
	s_nop 7
	v_max3_f32 v49, v49, v36, v37
	v_max3_f32 v49, v49, v38, v39
	ds_bpermute_b32 v58, v69, v49
	s_waitcnt lgkmcnt(0)
	v_max_f32_e32 v58, v58, v58
	v_max_f32_e32 v49, v49, v58
	ds_bpermute_b32 v58, v70, v49
	s_waitcnt lgkmcnt(0)
	v_max3_f32 v49, v85, v49, v58
	v_sub_f32_e32 v58, v85, v49
	v_mul_f32_e32 v58, 0x3fb8aa3b, v58
	v_exp_f32_e32 v58, v58
	s_nop 0
	v_cmp_neq_f32_e32 vcc, 1.0, v58
	s_cbranch_vccz .LBB0_171
	v_pk_mul_f32 v[14:15], v[14:15], v[58:59] op_sel_hi:[1,0]
	v_pk_mul_f32 v[12:13], v[12:13], v[58:59] op_sel_hi:[1,0]
	v_pk_mul_f32 v[18:19], v[18:19], v[58:59] op_sel_hi:[1,0]
	v_pk_mul_f32 v[16:17], v[16:17], v[58:59] op_sel_hi:[1,0]
	v_pk_mul_f32 v[22:23], v[22:23], v[58:59] op_sel_hi:[1,0]
	v_pk_mul_f32 v[20:21], v[20:21], v[58:59] op_sel_hi:[1,0]
	v_pk_mul_f32 v[10:11], v[10:11], v[58:59] op_sel_hi:[1,0]
	v_pk_mul_f32 v[8:9], v[8:9], v[58:59] op_sel_hi:[1,0]
